# v24 plus staged lgkmcnt waits inside the GEMM MFMA clusters (each MFMA waits only for the fragment reads it consumes)
# baseline (speedup 1.0000x reference)
.LBB0_204:
	s_add_u32 s44, s40, 0xfff80080
	s_addc_u32 s45, s41, -1
	s_and_b64 s[4:5], s[42:43], exec
	s_cselect_b32 s45, s31, s45
	s_cselect_b32 s44, s65, s44
	s_add_i32 s70, 0, 0x10000
	v_add_u32_e32 v168, s70, v145
	ds_read_b128 v[156:159], v168
	ds_read_b128 v[160:163], v168 offset:1024
	ds_read_b128 v[164:167], v168 offset:2048
	ds_read_b128 v[168:171], v168 offset:3072
	s_and_b64 s[4:5], s[42:43], exec
	s_cselect_b32 s5, s29, s68
	s_cselect_b32 s4, s66, s67
	v_lshl_add_u64 v[176:177], s[40:41], 0, v[136:137]
	s_add_i32 m0, s39, 0xc000
	ds_read_b128 v[172:175], v147
	ds_read_b128 v[180:183], v147 offset:1024
	ds_read_b128 v[184:187], v147 offset:2048
	ds_read_b128 v[188:191], v147 offset:3072
	ds_read_b128 v[192:195], v147 offset:4096
	ds_read_b128 v[216:219], v147 offset:5120
	ds_read_b128 v[220:223], v147 offset:6144
	ds_read_b128 v[224:227], v147 offset:7168
	global_load_lds_dwordx4 v[176:177], off
	v_lshl_add_u64 v[176:177], s[40:41], 0, v[138:139]
	s_add_i32 m0, s39, 0xe000
	s_nop 0
	global_load_lds_dwordx4 v[176:177], off
	s_waitcnt lgkmcnt(8)
	s_barrier
	s_waitcnt lgkmcnt(7)
	v_mfma_f32_16x16x32_bf16 v[126:129], v[156:159], v[172:175], v[126:129]
	v_mfma_f32_16x16x32_bf16 v[122:125], v[164:167], v[172:175], v[122:125]
	s_waitcnt lgkmcnt(5)
	v_mfma_f32_16x16x32_bf16 v[110:113], v[156:159], v[184:187], v[110:113]
	v_mfma_f32_16x16x32_bf16 v[106:109], v[164:167], v[184:187], v[106:109]
	s_waitcnt lgkmcnt(3)
	v_mfma_f32_16x16x32_bf16 v[94:97], v[156:159], v[192:195], v[94:97]
	v_mfma_f32_16x16x32_bf16 v[90:93], v[164:167], v[192:195], v[90:93]
	s_waitcnt lgkmcnt(1)
	v_mfma_f32_16x16x32_bf16 v[78:81], v[156:159], v[220:223], v[78:81]
	v_mfma_f32_16x16x32_bf16 v[74:77], v[164:167], v[220:223], v[74:77]
	v_mfma_f32_16x16x32_bf16 v[126:129], v[160:163], v[180:183], v[126:129]
	v_mfma_f32_16x16x32_bf16 v[122:125], v[168:171], v[180:183], v[122:125]
	v_mfma_f32_16x16x32_bf16 v[110:113], v[160:163], v[188:191], v[110:113]
	v_mfma_f32_16x16x32_bf16 v[106:109], v[168:171], v[188:191], v[106:109]
	v_mfma_f32_16x16x32_bf16 v[94:97], v[160:163], v[216:219], v[94:97]
	v_mfma_f32_16x16x32_bf16 v[90:93], v[168:171], v[216:219], v[90:93]
	s_waitcnt lgkmcnt(0)
	v_mfma_f32_16x16x32_bf16 v[78:81], v[160:163], v[224:227], v[78:81]
	v_mfma_f32_16x16x32_bf16 v[74:77], v[168:171], v[224:227], v[74:77]
	s_barrier
	s_add_i32 s71, 0, 0x14000
	v_add_u32_e32 v176, s71, v145
	s_add_i32 s42, s70, s56
	ds_read_b128 v[228:231], v176
	ds_read_b128 v[232:235], v176 offset:1024
	ds_read_b128 v[236:239], v176 offset:2048
	ds_read_b128 v[240:243], v176 offset:3072
	v_lshl_add_u64 v[176:177], s[4:5], 0, v[0:1]
	s_mov_b32 m0, s42
	v_lshl_add_u64 v[196:197], s[4:5], 0, v[134:135]
	global_load_lds_dwordx4 v[176:177], off
	s_add_i32 m0, s42, 0x2000
	s_nop 0
	global_load_lds_dwordx4 v[196:197], off
	s_barrier
	s_waitcnt lgkmcnt(3)
	v_mfma_f32_16x16x32_bf16 v[118:121], v[228:231], v[172:175], v[118:121]
	s_waitcnt lgkmcnt(1)
	v_mfma_f32_16x16x32_bf16 v[114:117], v[236:239], v[172:175], v[114:117]
	v_mfma_f32_16x16x32_bf16 v[102:105], v[228:231], v[184:187], v[102:105]
	v_mfma_f32_16x16x32_bf16 v[98:101], v[236:239], v[184:187], v[98:101]
	v_mfma_f32_16x16x32_bf16 v[86:89], v[228:231], v[192:195], v[86:89]
	v_mfma_f32_16x16x32_bf16 v[82:85], v[236:239], v[192:195], v[82:85]
	v_mfma_f32_16x16x32_bf16 v[70:73], v[228:231], v[220:223], v[70:73]
	v_mfma_f32_16x16x32_bf16 v[66:69], v[236:239], v[220:223], v[66:69]
	v_mfma_f32_16x16x32_bf16 v[118:121], v[232:235], v[180:183], v[118:121]
	s_waitcnt lgkmcnt(0)
	v_mfma_f32_16x16x32_bf16 v[114:117], v[240:243], v[180:183], v[114:117]
	v_mfma_f32_16x16x32_bf16 v[102:105], v[232:235], v[188:191], v[102:105]
	v_mfma_f32_16x16x32_bf16 v[98:101], v[240:243], v[188:191], v[98:101]
	v_mfma_f32_16x16x32_bf16 v[86:89], v[232:235], v[216:219], v[86:89]
	v_mfma_f32_16x16x32_bf16 v[82:85], v[240:243], v[216:219], v[82:85]
	v_mfma_f32_16x16x32_bf16 v[70:73], v[232:235], v[224:227], v[70:73]
	v_mfma_f32_16x16x32_bf16 v[66:69], v[240:243], v[224:227], v[66:69]
	s_mov_b32 m0, s39
	v_lshl_add_u64 v[200:201], s[44:45], 0, v[130:131]
	s_barrier
	ds_read_b128 v[172:175], v147 offset:16384
	ds_read_b128 v[180:183], v147 offset:17408
	ds_read_b128 v[184:187], v147 offset:18432
	ds_read_b128 v[188:191], v147 offset:19456
	ds_read_b128 v[192:195], v147 offset:20480
	ds_read_b128 v[216:219], v147 offset:21504
	ds_read_b128 v[220:223], v147 offset:22528
	ds_read_b128 v[224:227], v147 offset:23552
	global_load_lds_dwordx4 v[200:201], off
	v_lshl_add_u64 v[206:207], s[44:45], 0, v[132:133]
	s_mov_b32 m0, s59
	s_nop 0
	global_load_lds_dwordx4 v[206:207], off
	s_barrier
	s_waitcnt lgkmcnt(7)
	v_mfma_f32_16x16x32_bf16 v[62:65], v[156:159], v[172:175], v[62:65]
	v_mfma_f32_16x16x32_bf16 v[58:61], v[164:167], v[172:175], v[58:61]
	s_waitcnt lgkmcnt(5)
	v_mfma_f32_16x16x32_bf16 v[46:49], v[156:159], v[184:187], v[46:49]
	v_mfma_f32_16x16x32_bf16 v[42:45], v[164:167], v[184:187], v[42:45]
	s_waitcnt lgkmcnt(3)
	v_mfma_f32_16x16x32_bf16 v[30:33], v[156:159], v[192:195], v[30:33]
	v_mfma_f32_16x16x32_bf16 v[26:29], v[164:167], v[192:195], v[26:29]
	s_waitcnt lgkmcnt(1)
	v_mfma_f32_16x16x32_bf16 v[14:17], v[156:159], v[220:223], v[14:17]
	v_mfma_f32_16x16x32_bf16 v[10:13], v[164:167], v[220:223], v[10:13]
	v_mfma_f32_16x16x32_bf16 v[62:65], v[160:163], v[180:183], v[62:65]
	v_mfma_f32_16x16x32_bf16 v[58:61], v[168:171], v[180:183], v[58:61]
	v_mfma_f32_16x16x32_bf16 v[46:49], v[160:163], v[188:191], v[46:49]
	v_mfma_f32_16x16x32_bf16 v[42:45], v[168:171], v[188:191], v[42:45]
	v_mfma_f32_16x16x32_bf16 v[30:33], v[160:163], v[216:219], v[30:33]
	v_mfma_f32_16x16x32_bf16 v[26:29], v[168:171], v[216:219], v[26:29]
	s_waitcnt lgkmcnt(0)
	v_mfma_f32_16x16x32_bf16 v[14:17], v[160:163], v[224:227], v[14:17]
	v_mfma_f32_16x16x32_bf16 v[10:13], v[168:171], v[224:227], v[10:13]
	s_barrier
	s_add_u32 s42, s4, 0x80000
	s_addc_u32 s43, s5, 0
	s_add_i32 s70, s71, s56
	v_lshl_add_u64 v[156:157], s[42:43], 0, v[0:1]
	s_mov_b32 m0, s70
	s_nop 0
	global_load_lds_dwordx4 v[156:157], off
	v_lshl_add_u64 v[156:157], s[42:43], 0, v[134:135]
	s_add_i32 m0, s70, 0x2000
	s_nop 0
	global_load_lds_dwordx4 v[156:157], off
	s_waitcnt vmcnt(6)
	s_barrier
	v_mfma_f32_16x16x32_bf16 v[54:57], v[228:231], v[172:175], v[54:57]
	v_mfma_f32_16x16x32_bf16 v[50:53], v[236:239], v[172:175], v[50:53]
	v_mfma_f32_16x16x32_bf16 v[38:41], v[228:231], v[184:187], v[38:41]
	v_mfma_f32_16x16x32_bf16 v[34:37], v[236:239], v[184:187], v[34:37]
	v_mfma_f32_16x16x32_bf16 v[22:25], v[228:231], v[192:195], v[22:25]
	v_mfma_f32_16x16x32_bf16 v[18:21], v[236:239], v[192:195], v[18:21]
	v_mfma_f32_16x16x32_bf16 v[6:9], v[228:231], v[220:223], v[6:9]
	v_mfma_f32_16x16x32_bf16 v[2:5], v[236:239], v[220:223], v[2:5]
	v_mfma_f32_16x16x32_bf16 v[54:57], v[232:235], v[180:183], v[54:57]
	v_mfma_f32_16x16x32_bf16 v[50:53], v[240:243], v[180:183], v[50:53]
	v_mfma_f32_16x16x32_bf16 v[38:41], v[232:235], v[188:191], v[38:41]
	v_mfma_f32_16x16x32_bf16 v[34:37], v[240:243], v[188:191], v[34:37]
	v_mfma_f32_16x16x32_bf16 v[22:25], v[232:235], v[216:219], v[22:25]
	v_mfma_f32_16x16x32_bf16 v[18:21], v[240:243], v[216:219], v[18:21]
	v_mfma_f32_16x16x32_bf16 v[6:9], v[232:235], v[224:227], v[6:9]
	v_mfma_f32_16x16x32_bf16 v[2:5], v[240:243], v[224:227], v[2:5]
	s_add_i32 s70, 0, 0x18000
	v_add_u32_e32 v168, s70, v145
	s_barrier
	ds_read_b128 v[156:159], v168
	ds_read_b128 v[160:163], v168 offset:1024
	ds_read_b128 v[164:167], v168 offset:2048
	ds_read_b128 v[168:171], v168 offset:3072
	s_add_u32 s42, s44, 0x80000
	s_addc_u32 s43, s45, 0
	s_mov_b32 m0, s60
	v_lshl_add_u64 v[208:209], s[42:43], 0, v[130:131]
	ds_read_b128 v[172:175], v147 offset:32768
	ds_read_b128 v[180:183], v147 offset:33792
	ds_read_b128 v[184:187], v147 offset:34816
	ds_read_b128 v[188:191], v147 offset:35840
	ds_read_b128 v[192:195], v147 offset:36864
	ds_read_b128 v[216:219], v147 offset:37888
	ds_read_b128 v[220:223], v147 offset:38912
	ds_read_b128 v[224:227], v147 offset:39936
	global_load_lds_dwordx4 v[208:209], off
	v_lshl_add_u64 v[208:209], s[42:43], 0, v[132:133]
	s_mov_b32 m0, s61
	s_nop 0
	global_load_lds_dwordx4 v[208:209], off
	s_waitcnt lgkmcnt(8)
	s_barrier
	s_waitcnt lgkmcnt(7)
	v_mfma_f32_16x16x32_bf16 v[126:129], v[156:159], v[172:175], v[126:129]
	v_mfma_f32_16x16x32_bf16 v[122:125], v[164:167], v[172:175], v[122:125]
	s_waitcnt lgkmcnt(5)
	v_mfma_f32_16x16x32_bf16 v[110:113], v[156:159], v[184:187], v[110:113]
	v_mfma_f32_16x16x32_bf16 v[106:109], v[164:167], v[184:187], v[106:109]
	s_waitcnt lgkmcnt(3)
	v_mfma_f32_16x16x32_bf16 v[94:97], v[156:159], v[192:195], v[94:97]
	v_mfma_f32_16x16x32_bf16 v[90:93], v[164:167], v[192:195], v[90:93]
	s_waitcnt lgkmcnt(1)
	v_mfma_f32_16x16x32_bf16 v[78:81], v[156:159], v[220:223], v[78:81]
	v_mfma_f32_16x16x32_bf16 v[74:77], v[164:167], v[220:223], v[74:77]
	v_mfma_f32_16x16x32_bf16 v[126:129], v[160:163], v[180:183], v[126:129]
	v_mfma_f32_16x16x32_bf16 v[122:125], v[168:171], v[180:183], v[122:125]
	v_mfma_f32_16x16x32_bf16 v[110:113], v[160:163], v[188:191], v[110:113]
	v_mfma_f32_16x16x32_bf16 v[106:109], v[168:171], v[188:191], v[106:109]
	v_mfma_f32_16x16x32_bf16 v[94:97], v[160:163], v[216:219], v[94:97]
	v_mfma_f32_16x16x32_bf16 v[90:93], v[168:171], v[216:219], v[90:93]
	s_waitcnt lgkmcnt(0)
	v_mfma_f32_16x16x32_bf16 v[78:81], v[160:163], v[224:227], v[78:81]
	v_mfma_f32_16x16x32_bf16 v[74:77], v[168:171], v[224:227], v[74:77]
	s_barrier
	s_add_i32 s42, 0, 0x1c000
	s_add_i32 s43, s70, s56
	v_add_u32_e32 v179, s42, v145
	v_lshl_add_u64 v[176:177], v[176:177], 0, s[78:79]
	s_mov_b32 m0, s43
	ds_read_b128 v[228:231], v179
	ds_read_b128 v[232:235], v179 offset:1024
	ds_read_b128 v[236:239], v179 offset:2048
	ds_read_b128 v[240:243], v179 offset:3072
	global_load_lds_dwordx4 v[176:177], off
	v_lshl_add_u64 v[176:177], v[196:197], 0, s[78:79]
	s_add_i32 m0, s43, 0x2000
	s_nop 0
	global_load_lds_dwordx4 v[176:177], off
	s_barrier
	s_waitcnt lgkmcnt(3)
	v_mfma_f32_16x16x32_bf16 v[118:121], v[228:231], v[172:175], v[118:121]
	s_waitcnt lgkmcnt(1)
	v_mfma_f32_16x16x32_bf16 v[114:117], v[236:239], v[172:175], v[114:117]
	v_mfma_f32_16x16x32_bf16 v[102:105], v[228:231], v[184:187], v[102:105]
	v_mfma_f32_16x16x32_bf16 v[98:101], v[236:239], v[184:187], v[98:101]
	v_mfma_f32_16x16x32_bf16 v[86:89], v[228:231], v[192:195], v[86:89]
	v_mfma_f32_16x16x32_bf16 v[82:85], v[236:239], v[192:195], v[82:85]
	v_mfma_f32_16x16x32_bf16 v[70:73], v[228:231], v[220:223], v[70:73]
	v_mfma_f32_16x16x32_bf16 v[66:69], v[236:239], v[220:223], v[66:69]
	v_mfma_f32_16x16x32_bf16 v[118:121], v[232:235], v[180:183], v[118:121]
	s_waitcnt lgkmcnt(0)
	v_mfma_f32_16x16x32_bf16 v[114:117], v[240:243], v[180:183], v[114:117]
	v_mfma_f32_16x16x32_bf16 v[102:105], v[232:235], v[188:191], v[102:105]
	v_mfma_f32_16x16x32_bf16 v[98:101], v[240:243], v[188:191], v[98:101]
	v_mfma_f32_16x16x32_bf16 v[86:89], v[232:235], v[216:219], v[86:89]
	v_mfma_f32_16x16x32_bf16 v[82:85], v[240:243], v[216:219], v[82:85]
	v_mfma_f32_16x16x32_bf16 v[70:73], v[232:235], v[224:227], v[70:73]
	v_mfma_f32_16x16x32_bf16 v[66:69], v[240:243], v[224:227], v[66:69]
	s_mov_b32 m0, s62
	v_lshl_add_u64 v[176:177], v[200:201], 0, s[78:79]
	s_barrier
	ds_read_b128 v[172:175], v147 offset:49152
	ds_read_b128 v[180:183], v147 offset:50176
	ds_read_b128 v[184:187], v147 offset:51200
	ds_read_b128 v[188:191], v147 offset:52224
	ds_read_b128 v[192:195], v147 offset:53248
	ds_read_b128 v[216:219], v147 offset:54272
	ds_read_b128 v[220:223], v147 offset:55296
	ds_read_b128 v[224:227], v147 offset:56320
	global_load_lds_dwordx4 v[176:177], off
	v_lshl_add_u64 v[176:177], v[206:207], 0, s[78:79]
	s_mov_b32 m0, s63
	s_nop 0
	global_load_lds_dwordx4 v[176:177], off
	s_barrier
	s_waitcnt lgkmcnt(7)
	v_mfma_f32_16x16x32_bf16 v[62:65], v[156:159], v[172:175], v[62:65]
	v_mfma_f32_16x16x32_bf16 v[58:61], v[164:167], v[172:175], v[58:61]
	s_waitcnt lgkmcnt(5)
	v_mfma_f32_16x16x32_bf16 v[46:49], v[156:159], v[184:187], v[46:49]
	v_mfma_f32_16x16x32_bf16 v[42:45], v[164:167], v[184:187], v[42:45]
	s_waitcnt lgkmcnt(3)
	v_mfma_f32_16x16x32_bf16 v[30:33], v[156:159], v[192:195], v[30:33]
	v_mfma_f32_16x16x32_bf16 v[26:29], v[164:167], v[192:195], v[26:29]
	s_waitcnt lgkmcnt(1)
	v_mfma_f32_16x16x32_bf16 v[14:17], v[156:159], v[220:223], v[14:17]
	v_mfma_f32_16x16x32_bf16 v[10:13], v[164:167], v[220:223], v[10:13]
	v_mfma_f32_16x16x32_bf16 v[62:65], v[160:163], v[180:183], v[62:65]
	v_mfma_f32_16x16x32_bf16 v[58:61], v[168:171], v[180:183], v[58:61]
	v_mfma_f32_16x16x32_bf16 v[46:49], v[160:163], v[188:191], v[46:49]
	v_mfma_f32_16x16x32_bf16 v[42:45], v[168:171], v[188:191], v[42:45]
	v_mfma_f32_16x16x32_bf16 v[30:33], v[160:163], v[216:219], v[30:33]
	v_mfma_f32_16x16x32_bf16 v[26:29], v[168:171], v[216:219], v[26:29]
	s_waitcnt lgkmcnt(0)
	v_mfma_f32_16x16x32_bf16 v[14:17], v[160:163], v[224:227], v[14:17]
	v_mfma_f32_16x16x32_bf16 v[10:13], v[168:171], v[224:227], v[10:13]
	s_barrier
	s_add_u32 s4, s4, 0x80080
	s_addc_u32 s5, s5, 0
	s_add_i32 s42, s42, s56
	v_lshl_add_u64 v[156:157], s[4:5], 0, v[0:1]
	s_mov_b32 m0, s42
	s_nop 0
	global_load_lds_dwordx4 v[156:157], off
	v_lshl_add_u64 v[156:157], s[4:5], 0, v[134:135]
	s_add_i32 m0, s42, 0x2000
	s_nop 0
	global_load_lds_dwordx4 v[156:157], off
	s_waitcnt vmcnt(6)
	s_barrier
	v_mfma_f32_16x16x32_bf16 v[54:57], v[228:231], v[172:175], v[54:57]
	v_mfma_f32_16x16x32_bf16 v[50:53], v[236:239], v[172:175], v[50:53]
	v_mfma_f32_16x16x32_bf16 v[38:41], v[228:231], v[184:187], v[38:41]
	v_mfma_f32_16x16x32_bf16 v[34:37], v[236:239], v[184:187], v[34:37]
	v_mfma_f32_16x16x32_bf16 v[22:25], v[228:231], v[192:195], v[22:25]
	v_mfma_f32_16x16x32_bf16 v[18:21], v[236:239], v[192:195], v[18:21]
	v_mfma_f32_16x16x32_bf16 v[6:9], v[228:231], v[220:223], v[6:9]
	v_mfma_f32_16x16x32_bf16 v[2:5], v[236:239], v[220:223], v[2:5]
	v_mfma_f32_16x16x32_bf16 v[54:57], v[232:235], v[180:183], v[54:57]
	v_mfma_f32_16x16x32_bf16 v[50:53], v[240:243], v[180:183], v[50:53]
	v_mfma_f32_16x16x32_bf16 v[38:41], v[232:235], v[188:191], v[38:41]
	v_mfma_f32_16x16x32_bf16 v[34:37], v[240:243], v[188:191], v[34:37]
	v_mfma_f32_16x16x32_bf16 v[22:25], v[232:235], v[216:219], v[22:25]
	v_mfma_f32_16x16x32_bf16 v[18:21], v[240:243], v[216:219], v[18:21]
	v_mfma_f32_16x16x32_bf16 v[6:9], v[232:235], v[224:227], v[6:9]
	v_mfma_f32_16x16x32_bf16 v[2:5], v[240:243], v[224:227], v[2:5]
	s_add_i32 s69, s69, 2
	s_add_u32 s40, s40, 0x100
	s_addc_u32 s41, s41, 0
	s_add_u32 s67, s67, 0x100
	s_addc_u32 s68, s68, 0
	s_cmp_gt_u32 s69, 29
	s_barrier
	s_cbranch_scc1 .LBB0_200

.LBB0_847:
	s_add_u32 s24, s20, 0xfffe0080
	s_addc_u32 s25, s21, -1
	s_add_i32 s53, 0, 0x10000
	v_add_u32_e32 v140, s53, v143
	ds_read_b128 v[146:149], v140
	ds_read_b128 v[150:153], v140 offset:1024
	ds_read_b128 v[154:157], v140 offset:2048
	ds_read_b128 v[158:161], v140 offset:3072
	s_cmp_eq_u32 s52, 4
	s_cselect_b32 s27, s11, s25
	s_cselect_b32 s26, s48, s24
	s_cselect_b32 s25, s9, s51
	s_cselect_b32 s24, s49, s50
	v_lshl_add_u64 v[140:141], s[20:21], 0, v[136:137]
	s_add_i32 m0, s15, 0xc000
	ds_read_b128 v[162:165], v145
	ds_read_b128 v[166:169], v145 offset:1024
	ds_read_b128 v[170:173], v145 offset:2048
	ds_read_b128 v[174:177], v145 offset:3072
	ds_read_b128 v[180:183], v145 offset:4096
	ds_read_b128 v[184:187], v145 offset:5120
	ds_read_b128 v[188:191], v145 offset:6144
	ds_read_b128 v[192:195], v145 offset:7168
	global_load_lds_dwordx4 v[140:141], off
	v_lshl_add_u64 v[140:141], s[20:21], 0, v[138:139]
	s_add_i32 m0, s15, 0xe000
	s_nop 0
	global_load_lds_dwordx4 v[140:141], off
	s_waitcnt lgkmcnt(8)
	s_barrier
	s_waitcnt lgkmcnt(7)
	v_mfma_f32_16x16x32_bf16 v[126:129], v[146:149], v[162:165], v[126:129]
	v_mfma_f32_16x16x32_bf16 v[122:125], v[154:157], v[162:165], v[122:125]
	s_waitcnt lgkmcnt(5)
	v_mfma_f32_16x16x32_bf16 v[118:121], v[146:149], v[170:173], v[118:121]
	v_mfma_f32_16x16x32_bf16 v[110:113], v[154:157], v[170:173], v[110:113]
	s_waitcnt lgkmcnt(3)
	v_mfma_f32_16x16x32_bf16 v[102:105], v[146:149], v[180:183], v[102:105]
	v_mfma_f32_16x16x32_bf16 v[94:97], v[154:157], v[180:183], v[94:97]
	s_waitcnt lgkmcnt(1)
	v_mfma_f32_16x16x32_bf16 v[86:89], v[146:149], v[188:191], v[86:89]
	v_mfma_f32_16x16x32_bf16 v[78:81], v[154:157], v[188:191], v[78:81]
	v_mfma_f32_16x16x32_bf16 v[126:129], v[150:153], v[166:169], v[126:129]
	v_mfma_f32_16x16x32_bf16 v[122:125], v[158:161], v[166:169], v[122:125]
	v_mfma_f32_16x16x32_bf16 v[118:121], v[150:153], v[174:177], v[118:121]
	v_mfma_f32_16x16x32_bf16 v[110:113], v[158:161], v[174:177], v[110:113]
	v_mfma_f32_16x16x32_bf16 v[102:105], v[150:153], v[184:187], v[102:105]
	v_mfma_f32_16x16x32_bf16 v[94:97], v[158:161], v[184:187], v[94:97]
	s_waitcnt lgkmcnt(0)
	v_mfma_f32_16x16x32_bf16 v[86:89], v[150:153], v[192:195], v[86:89]
	v_mfma_f32_16x16x32_bf16 v[78:81], v[158:161], v[192:195], v[78:81]
	s_barrier
	s_add_i32 s56, 0, 0x14000
	v_add_u32_e32 v140, s56, v143
	s_add_i32 s53, s53, s36
	ds_read_b128 v[216:219], v140
	ds_read_b128 v[220:223], v140 offset:1024
	ds_read_b128 v[224:227], v140 offset:2048
	ds_read_b128 v[228:231], v140 offset:3072
	v_lshl_add_u64 v[140:141], s[24:25], 0, v[0:1]
	s_mov_b32 m0, s53
	v_lshl_add_u64 v[196:197], s[24:25], 0, v[130:131]
	global_load_lds_dwordx4 v[140:141], off
	s_add_i32 m0, s53, 0x2000
	s_nop 0
	global_load_lds_dwordx4 v[196:197], off
	s_barrier
	s_waitcnt lgkmcnt(3)
	v_mfma_f32_16x16x32_bf16 v[114:117], v[216:219], v[162:165], v[114:117]
	s_waitcnt lgkmcnt(1)
	v_mfma_f32_16x16x32_bf16 v[106:109], v[224:227], v[162:165], v[106:109]
	v_mfma_f32_16x16x32_bf16 v[98:101], v[216:219], v[170:173], v[98:101]
	v_mfma_f32_16x16x32_bf16 v[90:93], v[224:227], v[170:173], v[90:93]
	v_mfma_f32_16x16x32_bf16 v[82:85], v[216:219], v[180:183], v[82:85]
	v_mfma_f32_16x16x32_bf16 v[74:77], v[224:227], v[180:183], v[74:77]
	v_mfma_f32_16x16x32_bf16 v[70:73], v[216:219], v[188:191], v[70:73]
	v_mfma_f32_16x16x32_bf16 v[66:69], v[224:227], v[188:191], v[66:69]
	v_mfma_f32_16x16x32_bf16 v[114:117], v[220:223], v[166:169], v[114:117]
	s_waitcnt lgkmcnt(0)
	v_mfma_f32_16x16x32_bf16 v[106:109], v[228:231], v[166:169], v[106:109]
	v_mfma_f32_16x16x32_bf16 v[98:101], v[220:223], v[174:177], v[98:101]
	v_mfma_f32_16x16x32_bf16 v[90:93], v[228:231], v[174:177], v[90:93]
	v_mfma_f32_16x16x32_bf16 v[82:85], v[220:223], v[184:187], v[82:85]
	v_mfma_f32_16x16x32_bf16 v[74:77], v[228:231], v[184:187], v[74:77]
	v_mfma_f32_16x16x32_bf16 v[70:73], v[220:223], v[192:195], v[70:73]
	v_mfma_f32_16x16x32_bf16 v[66:69], v[228:231], v[192:195], v[66:69]
	s_mov_b32 m0, s15
	v_lshl_add_u64 v[200:201], s[26:27], 0, v[134:135]
	s_barrier
	ds_read_b128 v[162:165], v145 offset:16384
	ds_read_b128 v[166:169], v145 offset:17408
	ds_read_b128 v[170:173], v145 offset:18432
	ds_read_b128 v[174:177], v145 offset:19456
	ds_read_b128 v[180:183], v145 offset:20480
	ds_read_b128 v[184:187], v145 offset:21504
	ds_read_b128 v[188:191], v145 offset:22528
	ds_read_b128 v[192:195], v145 offset:23552
	global_load_lds_dwordx4 v[200:201], off
	v_lshl_add_u64 v[206:207], s[26:27], 0, v[132:133]
	s_mov_b32 m0, s40
	s_nop 0
	global_load_lds_dwordx4 v[206:207], off
	s_barrier
	s_waitcnt lgkmcnt(7)
	v_mfma_f32_16x16x32_bf16 v[62:65], v[146:149], v[162:165], v[62:65]
	v_mfma_f32_16x16x32_bf16 v[58:61], v[154:157], v[162:165], v[58:61]
	s_waitcnt lgkmcnt(5)
	v_mfma_f32_16x16x32_bf16 v[54:57], v[146:149], v[170:173], v[54:57]
	v_mfma_f32_16x16x32_bf16 v[46:49], v[154:157], v[170:173], v[46:49]
	s_waitcnt lgkmcnt(3)
	v_mfma_f32_16x16x32_bf16 v[38:41], v[146:149], v[180:183], v[38:41]
	v_mfma_f32_16x16x32_bf16 v[30:33], v[154:157], v[180:183], v[30:33]
	s_waitcnt lgkmcnt(1)
	v_mfma_f32_16x16x32_bf16 v[22:25], v[146:149], v[188:191], v[22:25]
	v_mfma_f32_16x16x32_bf16 v[14:17], v[154:157], v[188:191], v[14:17]
	v_mfma_f32_16x16x32_bf16 v[62:65], v[150:153], v[166:169], v[62:65]
	v_mfma_f32_16x16x32_bf16 v[58:61], v[158:161], v[166:169], v[58:61]
	v_mfma_f32_16x16x32_bf16 v[54:57], v[150:153], v[174:177], v[54:57]
	v_mfma_f32_16x16x32_bf16 v[46:49], v[158:161], v[174:177], v[46:49]
	v_mfma_f32_16x16x32_bf16 v[38:41], v[150:153], v[184:187], v[38:41]
	v_mfma_f32_16x16x32_bf16 v[30:33], v[158:161], v[184:187], v[30:33]
	s_waitcnt lgkmcnt(0)
	v_mfma_f32_16x16x32_bf16 v[22:25], v[150:153], v[192:195], v[22:25]
	v_mfma_f32_16x16x32_bf16 v[14:17], v[158:161], v[192:195], v[14:17]
	s_barrier
	s_add_u32 s54, s24, 0x20000
	s_addc_u32 s55, s25, 0
	s_add_i32 s53, s56, s36
	v_lshl_add_u64 v[146:147], s[54:55], 0, v[0:1]
	s_mov_b32 m0, s53
	s_nop 0
	global_load_lds_dwordx4 v[146:147], off
	v_lshl_add_u64 v[146:147], s[54:55], 0, v[130:131]
	s_add_i32 m0, s53, 0x2000
	s_nop 0
	global_load_lds_dwordx4 v[146:147], off
	s_waitcnt vmcnt(6)
	s_barrier
	v_mfma_f32_16x16x32_bf16 v[50:53], v[216:219], v[162:165], v[50:53]
	v_mfma_f32_16x16x32_bf16 v[42:45], v[224:227], v[162:165], v[42:45]
	v_mfma_f32_16x16x32_bf16 v[34:37], v[216:219], v[170:173], v[34:37]
	v_mfma_f32_16x16x32_bf16 v[26:29], v[224:227], v[170:173], v[26:29]
	v_mfma_f32_16x16x32_bf16 v[18:21], v[216:219], v[180:183], v[18:21]
	v_mfma_f32_16x16x32_bf16 v[10:13], v[224:227], v[180:183], v[10:13]
	v_mfma_f32_16x16x32_bf16 v[6:9], v[216:219], v[188:191], v[6:9]
	v_mfma_f32_16x16x32_bf16 v[2:5], v[224:227], v[188:191], v[2:5]
	v_mfma_f32_16x16x32_bf16 v[50:53], v[220:223], v[166:169], v[50:53]
	v_mfma_f32_16x16x32_bf16 v[42:45], v[228:231], v[166:169], v[42:45]
	v_mfma_f32_16x16x32_bf16 v[34:37], v[220:223], v[174:177], v[34:37]
	v_mfma_f32_16x16x32_bf16 v[26:29], v[228:231], v[174:177], v[26:29]
	v_mfma_f32_16x16x32_bf16 v[18:21], v[220:223], v[184:187], v[18:21]
	v_mfma_f32_16x16x32_bf16 v[10:13], v[228:231], v[184:187], v[10:13]
	v_mfma_f32_16x16x32_bf16 v[6:9], v[220:223], v[192:195], v[6:9]
	v_mfma_f32_16x16x32_bf16 v[2:5], v[228:231], v[192:195], v[2:5]
	s_add_i32 s53, 0, 0x18000
	v_add_u32_e32 v158, s53, v143
	s_barrier
	ds_read_b128 v[146:149], v158
	ds_read_b128 v[150:153], v158 offset:1024
	ds_read_b128 v[154:157], v158 offset:2048
	ds_read_b128 v[158:161], v158 offset:3072
	s_add_u32 s26, s26, 0x20000
	s_addc_u32 s27, s27, 0
	s_mov_b32 m0, s41
	v_lshl_add_u64 v[208:209], s[26:27], 0, v[134:135]
	ds_read_b128 v[162:165], v145 offset:32768
	ds_read_b128 v[166:169], v145 offset:33792
	ds_read_b128 v[170:173], v145 offset:34816
	ds_read_b128 v[174:177], v145 offset:35840
	ds_read_b128 v[180:183], v145 offset:36864
	ds_read_b128 v[184:187], v145 offset:37888
	ds_read_b128 v[188:191], v145 offset:38912
	ds_read_b128 v[192:195], v145 offset:39936
	global_load_lds_dwordx4 v[208:209], off
	v_lshl_add_u64 v[208:209], s[26:27], 0, v[132:133]
	s_mov_b32 m0, s42
	s_nop 0
	global_load_lds_dwordx4 v[208:209], off
	s_waitcnt lgkmcnt(8)
	s_barrier
	s_waitcnt lgkmcnt(7)
	v_mfma_f32_16x16x32_bf16 v[126:129], v[146:149], v[162:165], v[126:129]
	v_mfma_f32_16x16x32_bf16 v[122:125], v[154:157], v[162:165], v[122:125]
	s_waitcnt lgkmcnt(5)
	v_mfma_f32_16x16x32_bf16 v[118:121], v[146:149], v[170:173], v[118:121]
	v_mfma_f32_16x16x32_bf16 v[110:113], v[154:157], v[170:173], v[110:113]
	s_waitcnt lgkmcnt(3)
	v_mfma_f32_16x16x32_bf16 v[102:105], v[146:149], v[180:183], v[102:105]
	v_mfma_f32_16x16x32_bf16 v[94:97], v[154:157], v[180:183], v[94:97]
	s_waitcnt lgkmcnt(1)
	v_mfma_f32_16x16x32_bf16 v[86:89], v[146:149], v[188:191], v[86:89]
	v_mfma_f32_16x16x32_bf16 v[78:81], v[154:157], v[188:191], v[78:81]
	v_mfma_f32_16x16x32_bf16 v[126:129], v[150:153], v[166:169], v[126:129]
	v_mfma_f32_16x16x32_bf16 v[122:125], v[158:161], v[166:169], v[122:125]
	v_mfma_f32_16x16x32_bf16 v[118:121], v[150:153], v[174:177], v[118:121]
	v_mfma_f32_16x16x32_bf16 v[110:113], v[158:161], v[174:177], v[110:113]
	v_mfma_f32_16x16x32_bf16 v[102:105], v[150:153], v[184:187], v[102:105]
	v_mfma_f32_16x16x32_bf16 v[94:97], v[158:161], v[184:187], v[94:97]
	s_waitcnt lgkmcnt(0)
	v_mfma_f32_16x16x32_bf16 v[86:89], v[150:153], v[192:195], v[86:89]
	v_mfma_f32_16x16x32_bf16 v[78:81], v[158:161], v[192:195], v[78:81]
	s_barrier
	s_add_i32 s26, 0, 0x1c000
	s_add_i32 s27, s53, s36
	v_add_u32_e32 v179, s26, v143
	v_lshl_add_u64 v[140:141], v[140:141], 0, s[78:79]
	s_mov_b32 m0, s27
	ds_read_b128 v[216:219], v179
	ds_read_b128 v[220:223], v179 offset:1024
	ds_read_b128 v[224:227], v179 offset:2048
	ds_read_b128 v[228:231], v179 offset:3072
	global_load_lds_dwordx4 v[140:141], off
	v_lshl_add_u64 v[140:141], v[196:197], 0, s[78:79]
	s_add_i32 m0, s27, 0x2000
	s_nop 0
	global_load_lds_dwordx4 v[140:141], off
	s_barrier
	s_waitcnt lgkmcnt(3)
	v_mfma_f32_16x16x32_bf16 v[114:117], v[216:219], v[162:165], v[114:117]
	s_waitcnt lgkmcnt(1)
	v_mfma_f32_16x16x32_bf16 v[106:109], v[224:227], v[162:165], v[106:109]
	v_mfma_f32_16x16x32_bf16 v[98:101], v[216:219], v[170:173], v[98:101]
	v_mfma_f32_16x16x32_bf16 v[90:93], v[224:227], v[170:173], v[90:93]
	v_mfma_f32_16x16x32_bf16 v[82:85], v[216:219], v[180:183], v[82:85]
	v_mfma_f32_16x16x32_bf16 v[74:77], v[224:227], v[180:183], v[74:77]
	v_mfma_f32_16x16x32_bf16 v[70:73], v[216:219], v[188:191], v[70:73]
	v_mfma_f32_16x16x32_bf16 v[66:69], v[224:227], v[188:191], v[66:69]
	v_mfma_f32_16x16x32_bf16 v[114:117], v[220:223], v[166:169], v[114:117]
	s_waitcnt lgkmcnt(0)
	v_mfma_f32_16x16x32_bf16 v[106:109], v[228:231], v[166:169], v[106:109]
	v_mfma_f32_16x16x32_bf16 v[98:101], v[220:223], v[174:177], v[98:101]
	v_mfma_f32_16x16x32_bf16 v[90:93], v[228:231], v[174:177], v[90:93]
	v_mfma_f32_16x16x32_bf16 v[82:85], v[220:223], v[184:187], v[82:85]
	v_mfma_f32_16x16x32_bf16 v[74:77], v[228:231], v[184:187], v[74:77]
	v_mfma_f32_16x16x32_bf16 v[70:73], v[220:223], v[192:195], v[70:73]
	v_mfma_f32_16x16x32_bf16 v[66:69], v[228:231], v[192:195], v[66:69]
	s_mov_b32 m0, s45
	v_lshl_add_u64 v[140:141], v[200:201], 0, s[78:79]
	s_barrier
	ds_read_b128 v[162:165], v145 offset:49152
	ds_read_b128 v[166:169], v145 offset:50176
	ds_read_b128 v[170:173], v145 offset:51200
	ds_read_b128 v[174:177], v145 offset:52224
	ds_read_b128 v[180:183], v145 offset:53248
	ds_read_b128 v[184:187], v145 offset:54272
	ds_read_b128 v[188:191], v145 offset:55296
	ds_read_b128 v[192:195], v145 offset:56320
	global_load_lds_dwordx4 v[140:141], off
	v_lshl_add_u64 v[140:141], v[206:207], 0, s[78:79]
	s_mov_b32 m0, s46
	s_nop 0
	global_load_lds_dwordx4 v[140:141], off
	s_barrier
	s_waitcnt lgkmcnt(7)
	v_mfma_f32_16x16x32_bf16 v[62:65], v[146:149], v[162:165], v[62:65]
	v_mfma_f32_16x16x32_bf16 v[58:61], v[154:157], v[162:165], v[58:61]
	s_waitcnt lgkmcnt(5)
	v_mfma_f32_16x16x32_bf16 v[54:57], v[146:149], v[170:173], v[54:57]
	v_mfma_f32_16x16x32_bf16 v[46:49], v[154:157], v[170:173], v[46:49]
	s_waitcnt lgkmcnt(3)
	v_mfma_f32_16x16x32_bf16 v[38:41], v[146:149], v[180:183], v[38:41]
	v_mfma_f32_16x16x32_bf16 v[30:33], v[154:157], v[180:183], v[30:33]
	s_waitcnt lgkmcnt(1)
	v_mfma_f32_16x16x32_bf16 v[22:25], v[146:149], v[188:191], v[22:25]
	v_mfma_f32_16x16x32_bf16 v[14:17], v[154:157], v[188:191], v[14:17]
	v_mfma_f32_16x16x32_bf16 v[62:65], v[150:153], v[166:169], v[62:65]
	v_mfma_f32_16x16x32_bf16 v[58:61], v[158:161], v[166:169], v[58:61]
	v_mfma_f32_16x16x32_bf16 v[54:57], v[150:153], v[174:177], v[54:57]
	v_mfma_f32_16x16x32_bf16 v[46:49], v[158:161], v[174:177], v[46:49]
	v_mfma_f32_16x16x32_bf16 v[38:41], v[150:153], v[184:187], v[38:41]
	v_mfma_f32_16x16x32_bf16 v[30:33], v[158:161], v[184:187], v[30:33]
	s_waitcnt lgkmcnt(0)
	v_mfma_f32_16x16x32_bf16 v[22:25], v[150:153], v[192:195], v[22:25]
	v_mfma_f32_16x16x32_bf16 v[14:17], v[158:161], v[192:195], v[14:17]
	s_barrier
	s_add_u32 s24, s24, 0x20080
	s_addc_u32 s25, s25, 0
	s_add_i32 s26, s26, s36
	v_lshl_add_u64 v[140:141], s[24:25], 0, v[0:1]
	s_mov_b32 m0, s26
	s_nop 0
	global_load_lds_dwordx4 v[140:141], off
	v_lshl_add_u64 v[140:141], s[24:25], 0, v[130:131]
	s_add_i32 m0, s26, 0x2000
	s_nop 0
	global_load_lds_dwordx4 v[140:141], off
	s_waitcnt vmcnt(6)
	s_barrier
	v_mfma_f32_16x16x32_bf16 v[50:53], v[216:219], v[162:165], v[50:53]
	v_mfma_f32_16x16x32_bf16 v[42:45], v[224:227], v[162:165], v[42:45]
	v_mfma_f32_16x16x32_bf16 v[34:37], v[216:219], v[170:173], v[34:37]
	v_mfma_f32_16x16x32_bf16 v[26:29], v[224:227], v[170:173], v[26:29]
	v_mfma_f32_16x16x32_bf16 v[18:21], v[216:219], v[180:183], v[18:21]
	v_mfma_f32_16x16x32_bf16 v[10:13], v[224:227], v[180:183], v[10:13]
	v_mfma_f32_16x16x32_bf16 v[6:9], v[216:219], v[188:191], v[6:9]
	v_mfma_f32_16x16x32_bf16 v[2:5], v[224:227], v[188:191], v[2:5]
	v_mfma_f32_16x16x32_bf16 v[50:53], v[220:223], v[166:169], v[50:53]
	v_mfma_f32_16x16x32_bf16 v[42:45], v[228:231], v[166:169], v[42:45]
	v_mfma_f32_16x16x32_bf16 v[34:37], v[220:223], v[174:177], v[34:37]
	v_mfma_f32_16x16x32_bf16 v[26:29], v[228:231], v[174:177], v[26:29]
	v_mfma_f32_16x16x32_bf16 v[18:21], v[220:223], v[184:187], v[18:21]
	v_mfma_f32_16x16x32_bf16 v[10:13], v[228:231], v[184:187], v[10:13]
	v_mfma_f32_16x16x32_bf16 v[6:9], v[220:223], v[192:195], v[6:9]
	v_mfma_f32_16x16x32_bf16 v[2:5], v[228:231], v[192:195], v[2:5]
	s_add_i32 s52, s52, 2
	s_add_u32 s20, s20, 0x100
	s_addc_u32 s21, s21, 0
	s_add_u32 s50, s50, 0x100
	s_addc_u32 s51, s51, 0
	s_cmp_gt_u32 s52, 5
	s_barrier
	s_cbranch_scc0 .LBB0_847
	v_lshl_add_u32 v148, s14, 8, v142
	v_lshl_or_b32 v140, s47, 8, v144
	v_ashrrev_i32_e32 v141, 31, v140
	v_mad_i64_i32 v[146:147], s[20:21], s44, v148, 0
	v_lshl_add_u64 v[146:147], v[146:147], 1, s[6:7]
	v_lshlrev_b64 v[140:141], 1, v[140:141]
	v_lshl_add_u64 v[146:147], v[146:147], 0, v[140:141]
	v_cvt_pk_bf16_f32 v126, v126, v127
	v_cvt_pk_bf16_f32 v127, v128, v129
	v_cvt_pk_bf16_f32 v128, v122, v123
	v_cvt_pk_bf16_f32 v129, v124, v125
	global_store_dwordx4 v[146:147], v[126:129], off
	v_cvt_pk_bf16_f32 v114, v114, v115
	v_cvt_pk_bf16_f32 v115, v116, v117
	v_cvt_pk_bf16_f32 v116, v106, v107
	v_or_b32_e32 v106, 16, v148
	v_mad_i64_i32 v[106:107], s[20:21], s44, v106, 0
	v_lshl_add_u64 v[106:107], v[106:107], 1, s[6:7]
	v_cvt_pk_bf16_f32 v117, v108, v109
	global_store_dwordx4 v[146:147], v[114:117], off offset:256
	s_and_b64 vcc, exec, s[0:1]
	s_mov_b32 s47, s8
	v_lshl_add_u64 v[114:115], v[106:107], 0, v[140:141]
	v_cvt_pk_bf16_f32 v106, v118, v119
	v_cvt_pk_bf16_f32 v107, v120, v121
	v_cvt_pk_bf16_f32 v108, v110, v111
	v_cvt_pk_bf16_f32 v109, v112, v113
	global_store_dwordx4 v[114:115], v[106:109], off
	v_cvt_pk_bf16_f32 v98, v98, v99
	v_cvt_pk_bf16_f32 v99, v100, v101
	v_cvt_pk_bf16_f32 v100, v90, v91
	v_or_b32_e32 v90, 32, v148
	v_mad_i64_i32 v[90:91], s[20:21], s44, v90, 0
	v_lshl_add_u64 v[90:91], v[90:91], 1, s[6:7]
	v_cvt_pk_bf16_f32 v101, v92, v93
	global_store_dwordx4 v[114:115], v[98:101], off offset:256
	s_mov_b32 s14, s10
	s_mov_b64 s[24:25], s[18:19]
	v_lshl_add_u64 v[98:99], v[90:91], 0, v[140:141]
	v_cvt_pk_bf16_f32 v90, v102, v103
	v_cvt_pk_bf16_f32 v91, v104, v105
	v_cvt_pk_bf16_f32 v92, v94, v95
	v_cvt_pk_bf16_f32 v93, v96, v97
	global_store_dwordx4 v[98:99], v[90:93], off
	v_cvt_pk_bf16_f32 v82, v82, v83
	v_cvt_pk_bf16_f32 v83, v84, v85
	v_cvt_pk_bf16_f32 v84, v74, v75
	v_or_b32_e32 v74, 48, v148
	v_mad_i64_i32 v[74:75], s[20:21], s44, v74, 0
	v_lshl_add_u64 v[74:75], v[74:75], 1, s[6:7]
	v_cvt_pk_bf16_f32 v85, v76, v77
	global_store_dwordx4 v[98:99], v[82:85], off offset:256
	s_nop 1
	v_lshl_add_u64 v[82:83], v[74:75], 0, v[140:141]
	v_cvt_pk_bf16_f32 v74, v86, v87
	v_cvt_pk_bf16_f32 v75, v88, v89
	v_cvt_pk_bf16_f32 v76, v78, v79
	v_cvt_pk_bf16_f32 v77, v80, v81
	global_store_dwordx4 v[82:83], v[74:77], off
	v_cvt_pk_bf16_f32 v70, v70, v71
	v_cvt_pk_bf16_f32 v71, v72, v73
	v_cvt_pk_bf16_f32 v72, v66, v67
	v_add_u32_e32 v66, 0x80, v148
	v_mad_i64_i32 v[66:67], s[20:21], s44, v66, 0
	v_lshl_add_u64 v[66:67], v[66:67], 1, s[6:7]
	v_lshl_add_u64 v[66:67], v[66:67], 0, v[140:141]
	v_cvt_pk_bf16_f32 v73, v68, v69
	global_store_dwordx4 v[82:83], v[70:73], off offset:256
	v_cvt_pk_bf16_f32 v62, v62, v63
	v_cvt_pk_bf16_f32 v63, v64, v65
	v_cvt_pk_bf16_f32 v64, v58, v59
	v_cvt_pk_bf16_f32 v65, v60, v61
	global_store_dwordx4 v[66:67], v[62:65], off
	v_cvt_pk_bf16_f32 v50, v50, v51
	v_cvt_pk_bf16_f32 v51, v52, v53
	v_cvt_pk_bf16_f32 v52, v42, v43
	v_add_u32_e32 v42, 0x90, v148
	v_mad_i64_i32 v[42:43], s[20:21], s44, v42, 0
	v_lshl_add_u64 v[42:43], v[42:43], 1, s[6:7]
	v_cvt_pk_bf16_f32 v53, v44, v45
	global_store_dwordx4 v[66:67], v[50:53], off offset:256
	s_nop 1
	v_lshl_add_u64 v[50:51], v[42:43], 0, v[140:141]
	v_cvt_pk_bf16_f32 v42, v54, v55
	v_cvt_pk_bf16_f32 v43, v56, v57
	v_cvt_pk_bf16_f32 v44, v46, v47
	v_cvt_pk_bf16_f32 v45, v48, v49
	global_store_dwordx4 v[50:51], v[42:45], off
	v_cvt_pk_bf16_f32 v34, v34, v35
	v_cvt_pk_bf16_f32 v35, v36, v37
	v_cvt_pk_bf16_f32 v36, v26, v27
	v_add_u32_e32 v26, 0xa0, v148
	v_mad_i64_i32 v[26:27], s[20:21], s44, v26, 0
	v_lshl_add_u64 v[26:27], v[26:27], 1, s[6:7]
	v_cvt_pk_bf16_f32 v37, v28, v29
	global_store_dwordx4 v[50:51], v[34:37], off offset:256
	s_nop 1
	v_lshl_add_u64 v[34:35], v[26:27], 0, v[140:141]
	v_cvt_pk_bf16_f32 v26, v38, v39
	v_cvt_pk_bf16_f32 v27, v40, v41
	v_cvt_pk_bf16_f32 v28, v30, v31
	v_cvt_pk_bf16_f32 v29, v32, v33
	global_store_dwordx4 v[34:35], v[26:29], off
	v_cvt_pk_bf16_f32 v18, v18, v19
	v_cvt_pk_bf16_f32 v19, v20, v21
	v_cvt_pk_bf16_f32 v20, v10, v11
	v_add_u32_e32 v10, 0xb0, v148
	v_mad_i64_i32 v[10:11], s[20:21], s44, v10, 0
	v_lshl_add_u64 v[10:11], v[10:11], 1, s[6:7]
	v_cvt_pk_bf16_f32 v21, v12, v13
	global_store_dwordx4 v[34:35], v[18:21], off offset:256
	s_mov_b64 s[20:21], s[16:17]
	s_nop 0
	v_lshl_add_u64 v[18:19], v[10:11], 0, v[140:141]
	v_cvt_pk_bf16_f32 v10, v22, v23
	v_cvt_pk_bf16_f32 v11, v24, v25
	v_cvt_pk_bf16_f32 v12, v14, v15
	v_cvt_pk_bf16_f32 v13, v16, v17
	global_store_dwordx4 v[18:19], v[10:13], off
	v_cvt_pk_bf16_f32 v6, v6, v7
	v_cvt_pk_bf16_f32 v7, v8, v9
	v_cvt_pk_bf16_f32 v8, v2, v3
	v_cvt_pk_bf16_f32 v9, v4, v5
	global_store_dwordx4 v[18:19], v[6:9], off offset:256
	s_cbranch_vccz .LBB0_844
	s_waitcnt vmcnt(0)
	s_cmpk_gt_u32 s28, 0xff
	s_cbranch_scc1 .LBB0_838
	s_barrier
	s_branch .LBB0_838

.LBB0_1348:
	s_add_i32 s40, s14, 2
	s_add_u32 s16, s12, 0x80
	s_addc_u32 s15, s13, 0
	s_add_i32 s41, 0, 0x10000
	v_add_u32_e32 v126, s41, v216
	ds_read_b128 v[114:117], v126
	ds_read_b128 v[118:121], v126 offset:1024
	ds_read_b128 v[122:125], v126 offset:2048
	ds_read_b128 v[126:129], v126 offset:3072
	s_cmp_eq_u32 s30, s14
	s_cselect_b32 s14, s4, s16
	s_cselect_b32 s15, s5, s15
	s_cselect_b32 s17, s7, s39
	s_cselect_b32 s16, s6, s38
	v_lshl_add_u64 v[186:187], s[12:13], 0, v[182:183]
	s_add_i32 m0, s23, 0xc000
	ds_read_b128 v[130:133], v218
	ds_read_b128 v[134:137], v218 offset:1024
	ds_read_b128 v[138:141], v218 offset:2048
	ds_read_b128 v[142:145], v218 offset:3072
	ds_read_b128 v[154:157], v218 offset:4096
	ds_read_b128 v[162:165], v218 offset:5120
	ds_read_b128 v[170:173], v218 offset:6144
	ds_read_b128 v[174:177], v218 offset:7168
	global_load_lds_dwordx4 v[186:187], off
	v_lshl_add_u64 v[186:187], s[12:13], 0, v[184:185]
	s_add_i32 m0, s23, 0xe000
	s_nop 0
	global_load_lds_dwordx4 v[186:187], off
	s_waitcnt lgkmcnt(8)
	s_barrier
	s_waitcnt lgkmcnt(7)
	v_mfma_f32_16x16x32_bf16 v[166:169], v[114:117], v[130:133], v[166:169]
	v_mfma_f32_16x16x32_bf16 v[158:161], v[122:125], v[130:133], v[158:161]
	s_waitcnt lgkmcnt(5)
	v_mfma_f32_16x16x32_bf16 v[110:113], v[114:117], v[138:141], v[110:113]
	v_mfma_f32_16x16x32_bf16 v[106:109], v[122:125], v[138:141], v[106:109]
	s_waitcnt lgkmcnt(3)
	v_mfma_f32_16x16x32_bf16 v[94:97], v[114:117], v[154:157], v[94:97]
	v_mfma_f32_16x16x32_bf16 v[90:93], v[122:125], v[154:157], v[90:93]
	s_waitcnt lgkmcnt(1)
	v_mfma_f32_16x16x32_bf16 v[78:81], v[114:117], v[170:173], v[78:81]
	v_mfma_f32_16x16x32_bf16 v[74:77], v[122:125], v[170:173], v[74:77]
	v_mfma_f32_16x16x32_bf16 v[166:169], v[118:121], v[134:137], v[166:169]
	v_mfma_f32_16x16x32_bf16 v[158:161], v[126:129], v[134:137], v[158:161]
	v_mfma_f32_16x16x32_bf16 v[110:113], v[118:121], v[142:145], v[110:113]
	v_mfma_f32_16x16x32_bf16 v[106:109], v[126:129], v[142:145], v[106:109]
	v_mfma_f32_16x16x32_bf16 v[94:97], v[118:121], v[162:165], v[94:97]
	v_mfma_f32_16x16x32_bf16 v[90:93], v[126:129], v[162:165], v[90:93]
	s_waitcnt lgkmcnt(0)
	v_mfma_f32_16x16x32_bf16 v[78:81], v[118:121], v[174:177], v[78:81]
	v_mfma_f32_16x16x32_bf16 v[74:77], v[126:129], v[174:177], v[74:77]
	s_barrier
	s_add_i32 s42, 0, 0x14000
	s_add_i32 s41, s41, s22
	v_add_u32_e32 v199, s42, v216
	v_lshl_add_u64 v[200:201], s[16:17], 0, v[0:1]
	s_mov_b32 m0, s41
	ds_read_b128 v[186:189], v199
	ds_read_b128 v[190:193], v199 offset:1024
	ds_read_b128 v[194:197], v199 offset:2048
	ds_read_b128 v[206:209], v199 offset:3072
	global_load_lds_dwordx4 v[200:201], off
	v_lshl_add_u64 v[220:221], s[16:17], 0, v[180:181]
	s_add_i32 m0, s41, 0x2000
	s_nop 0
	global_load_lds_dwordx4 v[220:221], off
	s_barrier
	s_waitcnt lgkmcnt(3)
	v_mfma_f32_16x16x32_bf16 v[150:153], v[186:189], v[130:133], v[150:153]
	v_mfma_f32_16x16x32_bf16 v[102:105], v[186:189], v[138:141], v[102:105]
	s_waitcnt lgkmcnt(1)
	v_mfma_f32_16x16x32_bf16 v[98:101], v[194:197], v[138:141], v[98:101]
	v_mfma_f32_16x16x32_bf16 v[86:89], v[186:189], v[154:157], v[86:89]
	v_mfma_f32_16x16x32_bf16 v[82:85], v[194:197], v[154:157], v[82:85]
	v_mfma_f32_16x16x32_bf16 v[70:73], v[186:189], v[170:173], v[70:73]
	v_mfma_f32_16x16x32_bf16 v[66:69], v[194:197], v[170:173], v[66:69]
	v_mfma_f32_16x16x32_bf16 v[150:153], v[190:193], v[134:137], v[150:153]
	v_mfma_f32_16x16x32_bf16 v[130:133], v[194:197], v[130:133], v[146:149]
	v_mfma_f32_16x16x32_bf16 v[102:105], v[190:193], v[142:145], v[102:105]
	s_waitcnt lgkmcnt(0)
	v_mfma_f32_16x16x32_bf16 v[98:101], v[206:209], v[142:145], v[98:101]
	v_mfma_f32_16x16x32_bf16 v[86:89], v[190:193], v[162:165], v[86:89]
	v_mfma_f32_16x16x32_bf16 v[82:85], v[206:209], v[162:165], v[82:85]
	v_mfma_f32_16x16x32_bf16 v[70:73], v[190:193], v[174:177], v[70:73]
	v_mfma_f32_16x16x32_bf16 v[66:69], v[206:209], v[174:177], v[66:69]
	v_mfma_f32_16x16x32_bf16 v[130:133], v[206:209], v[134:137], v[130:133]
	s_mov_b32 m0, s23
	v_lshl_add_u64 v[222:223], s[14:15], 0, v[0:1]
	s_barrier
	ds_read_b128 v[134:137], v218 offset:16384
	ds_read_b128 v[138:141], v218 offset:17408
	ds_read_b128 v[142:145], v218 offset:18432
	ds_read_b128 v[146:149], v218 offset:19456
	ds_read_b128 v[154:157], v218 offset:20480
	ds_read_b128 v[162:165], v218 offset:21504
	ds_read_b128 v[170:173], v218 offset:22528
	ds_read_b128 v[174:177], v218 offset:23552
	global_load_lds_dwordx4 v[222:223], off
	v_lshl_add_u64 v[224:225], s[14:15], 0, v[180:181]
	s_mov_b32 m0, s24
	s_nop 0
	global_load_lds_dwordx4 v[224:225], off
	s_barrier
	s_waitcnt lgkmcnt(7)
	v_mfma_f32_16x16x32_bf16 v[62:65], v[114:117], v[134:137], v[62:65]
	v_mfma_f32_16x16x32_bf16 v[58:61], v[122:125], v[134:137], v[58:61]
	s_waitcnt lgkmcnt(5)
	v_mfma_f32_16x16x32_bf16 v[46:49], v[114:117], v[142:145], v[46:49]
	v_mfma_f32_16x16x32_bf16 v[42:45], v[122:125], v[142:145], v[42:45]
	s_waitcnt lgkmcnt(3)
	v_mfma_f32_16x16x32_bf16 v[30:33], v[114:117], v[154:157], v[30:33]
	v_mfma_f32_16x16x32_bf16 v[26:29], v[122:125], v[154:157], v[26:29]
	s_waitcnt lgkmcnt(1)
	v_mfma_f32_16x16x32_bf16 v[14:17], v[114:117], v[170:173], v[14:17]
	v_mfma_f32_16x16x32_bf16 v[10:13], v[122:125], v[170:173], v[10:13]
	v_mfma_f32_16x16x32_bf16 v[62:65], v[118:121], v[138:141], v[62:65]
	v_mfma_f32_16x16x32_bf16 v[58:61], v[126:129], v[138:141], v[58:61]
	v_mfma_f32_16x16x32_bf16 v[46:49], v[118:121], v[146:149], v[46:49]
	v_mfma_f32_16x16x32_bf16 v[42:45], v[126:129], v[146:149], v[42:45]
	v_mfma_f32_16x16x32_bf16 v[30:33], v[118:121], v[162:165], v[30:33]
	v_mfma_f32_16x16x32_bf16 v[26:29], v[126:129], v[162:165], v[26:29]
	s_waitcnt lgkmcnt(0)
	v_mfma_f32_16x16x32_bf16 v[14:17], v[118:121], v[174:177], v[14:17]
	v_mfma_f32_16x16x32_bf16 v[10:13], v[126:129], v[174:177], v[10:13]
	s_barrier
	s_add_u32 s16, s16, s2
	s_addc_u32 s17, s17, 0
	s_add_i32 s41, s42, s22
	v_lshl_add_u64 v[226:227], s[16:17], 0, v[0:1]
	s_mov_b32 m0, s41
	v_lshl_add_u64 v[228:229], s[16:17], 0, v[180:181]
	global_load_lds_dwordx4 v[226:227], off
	s_add_i32 m0, s41, 0x2000
	s_nop 0
	global_load_lds_dwordx4 v[228:229], off
	s_waitcnt vmcnt(6)
	s_barrier
	v_mfma_f32_16x16x32_bf16 v[54:57], v[186:189], v[134:137], v[54:57]
	v_mfma_f32_16x16x32_bf16 v[50:53], v[194:197], v[134:137], v[50:53]
	v_mfma_f32_16x16x32_bf16 v[38:41], v[186:189], v[142:145], v[38:41]
	v_mfma_f32_16x16x32_bf16 v[34:37], v[194:197], v[142:145], v[34:37]
	v_mfma_f32_16x16x32_bf16 v[22:25], v[186:189], v[154:157], v[22:25]
	v_mfma_f32_16x16x32_bf16 v[18:21], v[194:197], v[154:157], v[18:21]
	v_mfma_f32_16x16x32_bf16 v[6:9], v[186:189], v[170:173], v[6:9]
	v_mfma_f32_16x16x32_bf16 v[2:5], v[194:197], v[170:173], v[2:5]
	v_mfma_f32_16x16x32_bf16 v[54:57], v[190:193], v[138:141], v[54:57]
	v_mfma_f32_16x16x32_bf16 v[50:53], v[206:209], v[138:141], v[50:53]
	v_mfma_f32_16x16x32_bf16 v[38:41], v[190:193], v[146:149], v[38:41]
	v_mfma_f32_16x16x32_bf16 v[34:37], v[206:209], v[146:149], v[34:37]
	v_mfma_f32_16x16x32_bf16 v[22:25], v[190:193], v[162:165], v[22:25]
	v_mfma_f32_16x16x32_bf16 v[18:21], v[206:209], v[162:165], v[18:21]
	v_mfma_f32_16x16x32_bf16 v[6:9], v[190:193], v[174:177], v[6:9]
	v_mfma_f32_16x16x32_bf16 v[2:5], v[206:209], v[174:177], v[2:5]
	s_add_i32 s16, 0, 0x18000
	v_add_u32_e32 v126, s16, v216
	s_barrier
	ds_read_b128 v[114:117], v126
	ds_read_b128 v[118:121], v126 offset:1024
	ds_read_b128 v[122:125], v126 offset:2048
	ds_read_b128 v[126:129], v126 offset:3072
	s_add_u32 s14, s14, s2
	s_addc_u32 s15, s15, 0
	s_mov_b32 m0, s25
	v_lshl_add_u64 v[146:147], s[14:15], 0, v[0:1]
	ds_read_b128 v[134:137], v218 offset:32768
	ds_read_b128 v[138:141], v218 offset:33792
	ds_read_b128 v[142:145], v218 offset:34816
	ds_read_b128 v[154:157], v218 offset:35840
	ds_read_b128 v[162:165], v218 offset:36864
	ds_read_b128 v[170:173], v218 offset:37888
	ds_read_b128 v[174:177], v218 offset:38912
	ds_read_b128 v[186:189], v218 offset:39936
	global_load_lds_dwordx4 v[146:147], off
	v_lshl_add_u64 v[146:147], s[14:15], 0, v[180:181]
	s_mov_b32 m0, s26
	s_nop 0
	global_load_lds_dwordx4 v[146:147], off
	s_waitcnt lgkmcnt(8)
	s_barrier
	s_waitcnt lgkmcnt(7)
	v_mfma_f32_16x16x32_bf16 v[146:149], v[114:117], v[134:137], v[166:169]
	s_waitcnt lgkmcnt(6)
	v_mfma_f32_16x16x32_bf16 v[166:169], v[118:121], v[138:141], v[146:149]
	v_mfma_f32_16x16x32_bf16 v[146:149], v[122:125], v[134:137], v[158:161]
	s_waitcnt lgkmcnt(5)
	v_mfma_f32_16x16x32_bf16 v[110:113], v[114:117], v[142:145], v[110:113]
	v_mfma_f32_16x16x32_bf16 v[106:109], v[122:125], v[142:145], v[106:109]
	s_waitcnt lgkmcnt(3)
	v_mfma_f32_16x16x32_bf16 v[94:97], v[114:117], v[162:165], v[94:97]
	v_mfma_f32_16x16x32_bf16 v[90:93], v[122:125], v[162:165], v[90:93]
	s_waitcnt lgkmcnt(1)
	v_mfma_f32_16x16x32_bf16 v[78:81], v[114:117], v[174:177], v[78:81]
	v_mfma_f32_16x16x32_bf16 v[74:77], v[122:125], v[174:177], v[74:77]
	v_mfma_f32_16x16x32_bf16 v[158:161], v[126:129], v[138:141], v[146:149]
	v_mfma_f32_16x16x32_bf16 v[110:113], v[118:121], v[154:157], v[110:113]
	v_mfma_f32_16x16x32_bf16 v[106:109], v[126:129], v[154:157], v[106:109]
	v_mfma_f32_16x16x32_bf16 v[94:97], v[118:121], v[170:173], v[94:97]
	v_mfma_f32_16x16x32_bf16 v[90:93], v[126:129], v[170:173], v[90:93]
	s_waitcnt lgkmcnt(0)
	v_mfma_f32_16x16x32_bf16 v[78:81], v[118:121], v[186:189], v[78:81]
	v_mfma_f32_16x16x32_bf16 v[74:77], v[126:129], v[186:189], v[74:77]
	s_barrier
	s_add_i32 s14, 0, 0x1c000
	v_add_u32_e32 v146, s14, v216
	s_add_i32 s15, s16, s22
	ds_read_b128 v[190:193], v146
	ds_read_b128 v[194:197], v146 offset:1024
	ds_read_b128 v[206:209], v146 offset:2048
	ds_read_b128 v[210:213], v146 offset:3072
	v_lshl_add_u64 v[146:147], v[200:201], 0, s[78:79]
	s_mov_b32 m0, s15
	s_nop 0
	global_load_lds_dwordx4 v[146:147], off
	v_lshl_add_u64 v[146:147], v[220:221], 0, s[78:79]
	s_add_i32 m0, s15, 0x2000
	s_nop 0
	global_load_lds_dwordx4 v[146:147], off
	s_barrier
	s_waitcnt lgkmcnt(3)
	v_mfma_f32_16x16x32_bf16 v[146:149], v[190:193], v[134:137], v[150:153]
	s_waitcnt lgkmcnt(1)
	v_mfma_f32_16x16x32_bf16 v[130:133], v[206:209], v[134:137], v[130:133]
	v_mfma_f32_16x16x32_bf16 v[102:105], v[190:193], v[142:145], v[102:105]
	v_mfma_f32_16x16x32_bf16 v[98:101], v[206:209], v[142:145], v[98:101]
	v_mfma_f32_16x16x32_bf16 v[86:89], v[190:193], v[162:165], v[86:89]
	v_mfma_f32_16x16x32_bf16 v[82:85], v[206:209], v[162:165], v[82:85]
	v_mfma_f32_16x16x32_bf16 v[70:73], v[190:193], v[174:177], v[70:73]
	v_mfma_f32_16x16x32_bf16 v[66:69], v[206:209], v[174:177], v[66:69]
	v_mfma_f32_16x16x32_bf16 v[150:153], v[194:197], v[138:141], v[146:149]
	s_waitcnt lgkmcnt(0)
	v_mfma_f32_16x16x32_bf16 v[146:149], v[210:213], v[138:141], v[130:133]
	v_mfma_f32_16x16x32_bf16 v[102:105], v[194:197], v[154:157], v[102:105]
	v_mfma_f32_16x16x32_bf16 v[98:101], v[210:213], v[154:157], v[98:101]
	v_mfma_f32_16x16x32_bf16 v[86:89], v[194:197], v[170:173], v[86:89]
	v_mfma_f32_16x16x32_bf16 v[82:85], v[210:213], v[170:173], v[82:85]
	v_mfma_f32_16x16x32_bf16 v[70:73], v[194:197], v[186:189], v[70:73]
	v_mfma_f32_16x16x32_bf16 v[66:69], v[210:213], v[186:189], v[66:69]
	s_mov_b32 m0, s28
	v_lshl_add_u64 v[186:187], v[222:223], 0, s[78:79]
	s_barrier
	ds_read_b128 v[130:133], v218 offset:49152
	ds_read_b128 v[134:137], v218 offset:50176
	ds_read_b128 v[138:141], v218 offset:51200
	ds_read_b128 v[142:145], v218 offset:52224
	ds_read_b128 v[154:157], v218 offset:53248
	ds_read_b128 v[162:165], v218 offset:54272
	ds_read_b128 v[170:173], v218 offset:55296
	ds_read_b128 v[174:177], v218 offset:56320
	global_load_lds_dwordx4 v[186:187], off
	v_lshl_add_u64 v[186:187], v[224:225], 0, s[78:79]
	s_mov_b32 m0, s29
	s_nop 0
	global_load_lds_dwordx4 v[186:187], off
	s_barrier
	s_waitcnt lgkmcnt(7)
	v_mfma_f32_16x16x32_bf16 v[62:65], v[114:117], v[130:133], v[62:65]
	v_mfma_f32_16x16x32_bf16 v[58:61], v[122:125], v[130:133], v[58:61]
	s_waitcnt lgkmcnt(5)
	v_mfma_f32_16x16x32_bf16 v[46:49], v[114:117], v[138:141], v[46:49]
	v_mfma_f32_16x16x32_bf16 v[42:45], v[122:125], v[138:141], v[42:45]
	s_waitcnt lgkmcnt(3)
	v_mfma_f32_16x16x32_bf16 v[30:33], v[114:117], v[154:157], v[30:33]
	v_mfma_f32_16x16x32_bf16 v[26:29], v[122:125], v[154:157], v[26:29]
	s_waitcnt lgkmcnt(1)
	v_mfma_f32_16x16x32_bf16 v[14:17], v[114:117], v[170:173], v[14:17]
	v_mfma_f32_16x16x32_bf16 v[10:13], v[122:125], v[170:173], v[10:13]
	v_mfma_f32_16x16x32_bf16 v[62:65], v[118:121], v[134:137], v[62:65]
	v_mfma_f32_16x16x32_bf16 v[58:61], v[126:129], v[134:137], v[58:61]
	v_mfma_f32_16x16x32_bf16 v[46:49], v[118:121], v[142:145], v[46:49]
	v_mfma_f32_16x16x32_bf16 v[42:45], v[126:129], v[142:145], v[42:45]
	v_mfma_f32_16x16x32_bf16 v[30:33], v[118:121], v[162:165], v[30:33]
	v_mfma_f32_16x16x32_bf16 v[26:29], v[126:129], v[162:165], v[26:29]
	s_waitcnt lgkmcnt(0)
	v_mfma_f32_16x16x32_bf16 v[14:17], v[118:121], v[174:177], v[14:17]
	v_mfma_f32_16x16x32_bf16 v[10:13], v[126:129], v[174:177], v[10:13]
	s_barrier
	s_add_i32 s14, s14, s22
	v_lshl_add_u64 v[114:115], v[226:227], 0, s[78:79]
	s_mov_b32 m0, s14
	s_nop 0
	global_load_lds_dwordx4 v[114:115], off
	v_lshl_add_u64 v[114:115], v[228:229], 0, s[78:79]
	s_add_i32 m0, s14, 0x2000
	s_nop 0
	global_load_lds_dwordx4 v[114:115], off
	s_waitcnt vmcnt(6)
	s_barrier
	v_mfma_f32_16x16x32_bf16 v[54:57], v[190:193], v[130:133], v[54:57]
	v_mfma_f32_16x16x32_bf16 v[50:53], v[206:209], v[130:133], v[50:53]
	v_mfma_f32_16x16x32_bf16 v[38:41], v[190:193], v[138:141], v[38:41]
	v_mfma_f32_16x16x32_bf16 v[34:37], v[206:209], v[138:141], v[34:37]
	v_mfma_f32_16x16x32_bf16 v[22:25], v[190:193], v[154:157], v[22:25]
	v_mfma_f32_16x16x32_bf16 v[18:21], v[206:209], v[154:157], v[18:21]
	v_mfma_f32_16x16x32_bf16 v[6:9], v[190:193], v[170:173], v[6:9]
	v_mfma_f32_16x16x32_bf16 v[2:5], v[206:209], v[170:173], v[2:5]
	v_mfma_f32_16x16x32_bf16 v[54:57], v[194:197], v[134:137], v[54:57]
	v_mfma_f32_16x16x32_bf16 v[50:53], v[210:213], v[134:137], v[50:53]
	v_mfma_f32_16x16x32_bf16 v[38:41], v[194:197], v[142:145], v[38:41]
	v_mfma_f32_16x16x32_bf16 v[34:37], v[210:213], v[142:145], v[34:37]
	v_mfma_f32_16x16x32_bf16 v[22:25], v[194:197], v[162:165], v[22:25]
	v_mfma_f32_16x16x32_bf16 v[18:21], v[210:213], v[162:165], v[18:21]
	v_mfma_f32_16x16x32_bf16 v[6:9], v[194:197], v[174:177], v[6:9]
	v_mfma_f32_16x16x32_bf16 v[2:5], v[210:213], v[174:177], v[2:5]
	s_add_u32 s12, s12, 0x100
	s_addc_u32 s13, s13, 0
	s_add_u32 s38, s38, 0x100
	s_addc_u32 s39, s39, 0
	s_cmp_ge_u32 s40, s27
	s_mov_b32 s14, s40
	s_barrier
	s_cbranch_scc0 .LBB0_1348
	v_readlane_b32 s100, v254, 20
	s_nop 1
	s_cmp_lg_u32 s100, 3
	s_cselect_b64 s[100:101], -1, 0
	s_and_b64 s[0:1], s[0:1], s[100:101]
	v_lshl_add_u32 v190, s37, 8, v179
	v_lshl_or_b32 v186, s36, 8, v217
	v_ashrrev_i32_e32 v187, 31, v186
	v_ashrrev_i32_e32 v191, 31, v190
	v_lshl_add_u64 v[188:189], v[186:187], 2, s[10:11]
	v_lshlrev_b64 v[114:115], 13, v[190:191]
	v_lshl_add_u64 v[114:115], v[188:189], 0, v[114:115]
	global_load_dwordx4 v[206:209], v[114:115], off
	global_load_dwordx4 v[210:213], v[114:115], off offset:64
	global_load_dwordx4 v[220:223], v[114:115], off offset:512
	global_load_dwordx4 v[224:227], v[114:115], off offset:576
	v_or_b32_e32 v196, 16, v190
	v_ashrrev_i32_e32 v197, 31, v196
	v_lshlrev_b64 v[114:115], 13, v[196:197]
	v_or_b32_e32 v194, 32, v190
	v_lshl_add_u64 v[114:115], v[188:189], 0, v[114:115]
	v_ashrrev_i32_e32 v195, 31, v194
	global_load_dwordx4 v[174:177], v[114:115], off
	global_load_dwordx4 v[170:173], v[114:115], off offset:64
	global_load_dwordx4 v[162:165], v[114:115], off offset:512
	global_load_dwordx4 v[154:157], v[114:115], off offset:576
	v_lshlrev_b64 v[114:115], 13, v[194:195]
	v_or_b32_e32 v192, 48, v190
	v_lshl_add_u64 v[114:115], v[188:189], 0, v[114:115]
	v_ashrrev_i32_e32 v193, 31, v192
	global_load_dwordx4 v[142:145], v[114:115], off
	global_load_dwordx4 v[138:141], v[114:115], off offset:64
	global_load_dwordx4 v[130:133], v[114:115], off offset:512
	global_load_dwordx4 v[122:125], v[114:115], off offset:576
	v_lshlrev_b64 v[114:115], 13, v[192:193]
	v_lshl_add_u64 v[114:115], v[188:189], 0, v[114:115]
	global_load_dwordx4 v[134:137], v[114:115], off
	global_load_dwordx4 v[126:129], v[114:115], off offset:64
	global_load_dwordx4 v[118:121], v[114:115], off offset:512
	s_nop 0
	global_load_dwordx4 v[114:117], v[114:115], off offset:576
	v_lshlrev_b64 v[200:201], 11, v[190:191]
	v_lshl_add_u64 v[200:201], v[200:201], 0, v[186:187]
	v_readlane_b32 s12, v252, 35
	v_readlane_b32 s13, v252, 36
	s_waitcnt vmcnt(0)
	v_pk_add_f32 v[166:167], v[166:167], v[206:207]
	s_nop 0
	v_mul_f32_e32 v199, v167, v167
	v_pk_add_f32 v[168:169], v[168:169], v[208:209]
	v_fmac_f32_e32 v199, v166, v166
	v_lshl_add_u64 v[206:207], v[200:201], 2, s[72:73]
	v_fmac_f32_e32 v199, v168, v168
	global_store_dwordx4 v[206:207], v[166:169], off
	v_fmac_f32_e32 v199, v169, v169
	v_pk_add_f32 v[158:159], v[158:159], v[210:211]
	v_cvt_pk_bf16_f32 v166, v166, v167
	v_cvt_pk_bf16_f32 v167, v168, v169
	v_lshlrev_b64 v[168:169], 1, v[200:201]
	v_lshl_add_u64 v[200:201], s[12:13], 0, v[168:169]
	s_mov_b64 exec, s[100:101]
	global_store_dwordx2 v[200:201], v[166:167], off
	s_mov_b64 exec, -1
	v_mul_f32_e32 v166, v159, v159
	v_pk_add_f32 v[160:161], v[160:161], v[212:213]
	v_fmac_f32_e32 v166, v158, v158
	v_fmac_f32_e32 v166, v160, v160
	global_store_dwordx4 v[206:207], v[158:161], off offset:64
	v_fmac_f32_e32 v166, v161, v161
	v_pk_add_f32 v[150:151], v[150:151], v[220:221]
	v_cvt_pk_bf16_f32 v158, v158, v159
	v_cvt_pk_bf16_f32 v159, v160, v161
	v_or_b32_e32 v160, 32, v168
	v_mov_b32_e32 v161, v169
	v_lshl_add_u64 v[160:161], s[12:13], 0, v[160:161]
	s_mov_b64 exec, s[100:101]
	global_store_dwordx2 v[160:161], v[158:159], off
	s_mov_b64 exec, -1
	v_mul_f32_e32 v158, v151, v151
	v_pk_add_f32 v[152:153], v[152:153], v[222:223]
	v_fmac_f32_e32 v158, v150, v150
	v_fmac_f32_e32 v158, v152, v152
	global_store_dwordx4 v[206:207], v[150:153], off offset:512
	v_fmac_f32_e32 v158, v153, v153
	v_pk_add_f32 v[146:147], v[146:147], v[224:225]
	v_cvt_pk_bf16_f32 v150, v150, v151
	v_cvt_pk_bf16_f32 v151, v152, v153
	v_or_b32_e32 v152, 0x100, v168
	v_mov_b32_e32 v153, v169
	v_lshl_add_u64 v[152:153], s[12:13], 0, v[152:153]
	s_mov_b64 exec, s[100:101]
	global_store_dwordx2 v[152:153], v[150:151], off
	s_mov_b64 exec, -1
	v_mul_f32_e32 v150, v147, v147
	v_pk_add_f32 v[148:149], v[148:149], v[226:227]
	v_fmac_f32_e32 v150, v146, v146
	v_fmac_f32_e32 v150, v148, v148
	v_or_b32_e32 v168, 0x120, v168
	global_store_dwordx4 v[206:207], v[146:149], off offset:576
	v_fmac_f32_e32 v150, v149, v149
	v_add_f32_e32 v166, v199, v166
	v_cvt_pk_bf16_f32 v146, v146, v147
	v_cvt_pk_bf16_f32 v147, v148, v149
	v_lshl_add_u64 v[148:149], s[12:13], 0, v[168:169]
	s_mov_b64 exec, s[100:101]
	global_store_dwordx2 v[148:149], v[146:147], off
	s_mov_b64 exec, -1
	v_and_b32_e32 v147, 64, v205
	v_xor_b32_e32 v146, 16, v205
	v_add_u32_e32 v147, 64, v147
	v_cmp_lt_i32_e32 vcc, v146, v147
	v_add_f32_e32 v158, v166, v158
	v_add_f32_e32 v150, v158, v150
	v_cndmask_b32_e32 v146, v205, v146, vcc
	v_lshlrev_b32_e32 v166, 2, v146
	ds_bpermute_b32 v146, v166, v150
	v_xor_b32_e32 v148, 32, v205
	v_cmp_lt_i32_e32 vcc, v148, v147
	s_waitcnt lgkmcnt(0)
	v_add_f32_e32 v146, v150, v146
	v_cndmask_b32_e32 v147, v205, v148, vcc
	v_lshlrev_b32_e32 v167, 2, v147
	ds_bpermute_b32 v147, v167, v146
	s_and_saveexec_b64 s[12:13], s[0:1]
	s_cbranch_execz .LBB0_1351
	v_readlane_b32 s14, v252, 28
	v_readlane_b32 s15, v252, 29
	s_waitcnt lgkmcnt(0)
	v_add_f32_e32 v146, v146, v147
	v_lshl_add_u64 v[148:149], v[190:191], 2, s[14:15]
	global_atomic_add_f32 v[148:149], v146, off
